# weight-prep tile stores (f32 to bf16 conversion phases) also issued write-through
# speedup vs baseline: 1.0070x; 1.0070x over previous
.LBB0_1169:
	v_cndmask_b32_e64 v3, v4, 0, s[8:9]
	v_cndmask_b32_e64 v4, v5, 0, s[8:9]
	v_cvt_pk_bf16_f32 v2, v6, v7
	v_cvt_pk_bf16_f32 v3, v3, v4
	ds_write2_b32 v24, v2, v3 offset0:112 offset1:120
	v_lshlrev_b32_e32 v2, 4, v26
	s_ashr_i32 s5, s4, 31
	v_and_b32_e32 v152, 0x1f0, v2
	s_lshl_b64 s[4:5], s[4:5], 1
	v_add_u32_e32 v8, 0, v152
	v_lshl_add_u64 v[0:1], v[0:1], 0, s[4:5]
	v_add_u32_e32 v4, v28, v29
	v_lshl_add_u64 v[10:11], v[0:1], 0, v[152:153]
	v_mad_u64_u32 v[0:1], s[4:5], v29, s69, v[8:9]
	v_ashrrev_i32_e32 v5, 31, v4
	s_waitcnt lgkmcnt(0)
	s_barrier
	ds_read_b128 v[0:3], v0
	v_mul_lo_u32 v6, s14, v5
	v_mul_lo_u32 v7, s15, v4
	v_mad_u64_u32 v[4:5], s[4:5], s14, v4, 0
	v_add3_u32 v5, v5, v6, v7
	v_lshl_add_u64 v[12:13], v[4:5], 1, v[10:11]
	v_add_u32_e32 v4, 0x200, v26
	v_ashrrev_i32_e32 v9, 5, v4
	v_mad_u64_u32 v[4:5], s[4:5], v9, s69, v[8:9]
	ds_read_b128 v[4:7], v4
	s_waitcnt lgkmcnt(1)
	global_store_dwordx4 v[12:13], v[0:3], off sc1
	s_add_i32 s2, s2, s34
	s_cmpk_lt_i32 s2, 0x758
	v_add_u32_e32 v0, v28, v9
	v_ashrrev_i32_e32 v1, 31, v0
	v_mul_lo_u32 v2, s14, v1
	v_mul_lo_u32 v3, s15, v0
	v_mad_u64_u32 v[0:1], s[4:5], s14, v0, 0
	v_add3_u32 v1, v1, v2, v3
	v_lshl_add_u64 v[0:1], v[0:1], 1, v[10:11]
	s_waitcnt lgkmcnt(0)
	global_store_dwordx4 v[0:1], v[4:7], off sc1
	v_add_u32_e32 v0, 0x400, v26
	s_nop 0
	v_ashrrev_i32_e32 v4, 5, v0
	v_mad_u64_u32 v[0:1], s[4:5], v4, s69, v[8:9]
	v_add_u32_e32 v4, v28, v4
	v_ashrrev_i32_e32 v5, 31, v4
	ds_read_b128 v[0:3], v0
	v_mul_lo_u32 v6, s14, v5
	v_mul_lo_u32 v7, s15, v4
	v_mad_u64_u32 v[4:5], s[4:5], s14, v4, 0
	v_add3_u32 v5, v5, v6, v7
	v_lshl_add_u64 v[12:13], v[4:5], 1, v[10:11]
	v_add_u32_e32 v4, 0x600, v26
	v_ashrrev_i32_e32 v9, 5, v4
	v_mad_u64_u32 v[4:5], s[4:5], v9, s69, v[8:9]
	ds_read_b128 v[4:7], v4
	s_waitcnt lgkmcnt(1)
	global_store_dwordx4 v[12:13], v[0:3], off sc1
	s_nop 1
	v_add_u32_e32 v0, v28, v9
	v_ashrrev_i32_e32 v1, 31, v0
	v_mul_lo_u32 v2, s14, v1
	v_mul_lo_u32 v3, s15, v0
	v_mad_u64_u32 v[0:1], s[4:5], s14, v0, 0
	v_add3_u32 v1, v1, v2, v3
	v_lshl_add_u64 v[0:1], v[0:1], 1, v[10:11]
	s_waitcnt lgkmcnt(0)
	global_store_dwordx4 v[0:1], v[4:7], off sc1
	s_barrier
	s_cbranch_scc0 .LBB0_1155

.LBB0_1291:
	v_cndmask_b32_e64 v3, v4, 0, s[8:9]
	v_cndmask_b32_e64 v4, v5, 0, s[8:9]
	v_cvt_pk_bf16_f32 v2, v6, v7
	v_cvt_pk_bf16_f32 v3, v3, v4
	ds_write2_b32 v24, v2, v3 offset0:112 offset1:120
	v_lshlrev_b32_e32 v2, 4, v26
	s_ashr_i32 s5, s4, 31
	v_and_b32_e32 v152, 0x1f0, v2
	s_lshl_b64 s[4:5], s[4:5], 1
	v_add_u32_e32 v8, 0, v152
	v_lshl_add_u64 v[0:1], v[0:1], 0, s[4:5]
	v_add_u32_e32 v4, v28, v29
	v_lshl_add_u64 v[10:11], v[0:1], 0, v[152:153]
	v_mad_u64_u32 v[0:1], s[4:5], v29, s69, v[8:9]
	v_ashrrev_i32_e32 v5, 31, v4
	s_waitcnt lgkmcnt(0)
	s_barrier
	ds_read_b128 v[0:3], v0
	v_mul_lo_u32 v6, s14, v5
	v_mul_lo_u32 v7, s15, v4
	v_mad_u64_u32 v[4:5], s[4:5], s14, v4, 0
	v_add3_u32 v5, v5, v6, v7
	v_lshl_add_u64 v[12:13], v[4:5], 1, v[10:11]
	v_add_u32_e32 v4, 0x200, v26
	v_ashrrev_i32_e32 v9, 5, v4
	v_mad_u64_u32 v[4:5], s[4:5], v9, s69, v[8:9]
	ds_read_b128 v[4:7], v4
	s_waitcnt lgkmcnt(1)
	global_store_dwordx4 v[12:13], v[0:3], off sc1
	s_nop 1
	v_add_u32_e32 v0, v28, v9
	v_ashrrev_i32_e32 v1, 31, v0
	v_mul_lo_u32 v2, s14, v1
	v_mul_lo_u32 v3, s15, v0
	v_mad_u64_u32 v[0:1], s[4:5], s14, v0, 0
	v_add3_u32 v1, v1, v2, v3
	v_lshl_add_u64 v[0:1], v[0:1], 1, v[10:11]
	s_waitcnt lgkmcnt(0)
	global_store_dwordx4 v[0:1], v[4:7], off sc1
	v_add_u32_e32 v0, 0x400, v26
	s_nop 0
	v_ashrrev_i32_e32 v4, 5, v0
	v_mad_u64_u32 v[0:1], s[4:5], v4, s69, v[8:9]
	v_add_u32_e32 v4, v28, v4
	v_ashrrev_i32_e32 v5, 31, v4
	ds_read_b128 v[0:3], v0
	v_mul_lo_u32 v6, s14, v5
	v_mul_lo_u32 v7, s15, v4
	v_mad_u64_u32 v[4:5], s[4:5], s14, v4, 0
	v_add3_u32 v5, v5, v6, v7
	v_lshl_add_u64 v[12:13], v[4:5], 1, v[10:11]
	v_add_u32_e32 v4, 0x600, v26
	v_ashrrev_i32_e32 v9, 5, v4
	v_mad_u64_u32 v[4:5], s[4:5], v9, s69, v[8:9]
	ds_read_b128 v[4:7], v4
	s_waitcnt lgkmcnt(1)
	global_store_dwordx4 v[12:13], v[0:3], off sc1
	s_nop 1
	v_add_u32_e32 v0, v28, v9
	v_ashrrev_i32_e32 v1, 31, v0
	v_mul_lo_u32 v2, s14, v1
	v_mul_lo_u32 v3, s15, v0
	v_mad_u64_u32 v[0:1], s[4:5], s14, v0, 0
	v_add3_u32 v1, v1, v2, v3
	s_add_i32 s4, s2, 0xe0
	v_lshl_add_u64 v[0:1], v[0:1], 1, v[10:11]
	s_cmpk_gt_i32 s2, 0x61f
	s_mov_b32 s2, s4
	s_waitcnt lgkmcnt(0)
	global_store_dwordx4 v[0:1], v[4:7], off sc1
	s_barrier
	s_cbranch_scc1 .LBB0_1161

.LBB0_1413:
	v_cndmask_b32_e64 v0, v0, 0, s[8:9]
	v_cndmask_b32_e64 v1, v1, 0, s[8:9]
	v_cvt_pk_bf16_f32 v2, v4, v5
	v_cvt_pk_bf16_f32 v0, v0, v1
	ds_write2_b32 v20, v2, v0 offset0:112 offset1:120
	v_lshlrev_b32_e32 v0, 4, v22
	s_lshl_b64 s[4:5], s[2:3], 1
	v_and_b32_e32 v152, 0x1f0, v0
	s_add_u32 s4, s16, s4
	v_add_u32_e32 v8, 0, v152
	s_addc_u32 s5, s17, s5
	v_add_u32_e32 v4, v23, v25
	v_lshl_add_u64 v[10:11], s[4:5], 0, v[152:153]
	v_mad_u64_u32 v[0:1], s[4:5], v25, s69, v[8:9]
	v_ashrrev_i32_e32 v5, 31, v4
	s_waitcnt lgkmcnt(0)
	s_barrier
	ds_read_b128 v[0:3], v0
	v_mul_lo_u32 v6, s14, v5
	v_mul_lo_u32 v7, s15, v4
	v_mad_u64_u32 v[4:5], s[4:5], s14, v4, 0
	v_add3_u32 v5, v5, v6, v7
	v_lshl_add_u64 v[12:13], v[4:5], 1, v[10:11]
	v_add_u32_e32 v4, 0x200, v22
	v_ashrrev_i32_e32 v9, 5, v4
	v_mad_u64_u32 v[4:5], s[4:5], v9, s69, v[8:9]
	ds_read_b128 v[4:7], v4
	s_waitcnt lgkmcnt(1)
	global_store_dwordx4 v[12:13], v[0:3], off sc1
	s_add_i32 s27, s27, 32
	s_add_i32 s26, s26, 32
	v_add_u32_e32 v0, v23, v9
	v_ashrrev_i32_e32 v1, 31, v0
	v_mul_lo_u32 v2, s14, v1
	v_mul_lo_u32 v3, s15, v0
	v_mad_u64_u32 v[0:1], s[4:5], s14, v0, 0
	v_add3_u32 v1, v1, v2, v3
	v_lshl_add_u64 v[0:1], v[0:1], 1, v[10:11]
	s_waitcnt lgkmcnt(0)
	global_store_dwordx4 v[0:1], v[4:7], off sc1
	v_add_u32_e32 v0, 0x400, v22
	s_cmpk_gt_i32 s28, 0x737
	v_ashrrev_i32_e32 v4, 5, v0
	v_mad_u64_u32 v[0:1], s[4:5], v4, s69, v[8:9]
	v_add_u32_e32 v4, v23, v4
	v_ashrrev_i32_e32 v5, 31, v4
	ds_read_b128 v[0:3], v0
	v_mul_lo_u32 v6, s14, v5
	v_mul_lo_u32 v7, s15, v4
	v_mad_u64_u32 v[4:5], s[4:5], s14, v4, 0
	v_add3_u32 v5, v5, v6, v7
	v_lshl_add_u64 v[12:13], v[4:5], 1, v[10:11]
	v_add_u32_e32 v4, 0x600, v22
	v_ashrrev_i32_e32 v9, 5, v4
	v_mad_u64_u32 v[4:5], s[4:5], v9, s69, v[8:9]
	ds_read_b128 v[4:7], v4
	s_waitcnt lgkmcnt(1)
	global_store_dwordx4 v[12:13], v[0:3], off sc1
	s_nop 1
	v_add_u32_e32 v0, v23, v9
	v_ashrrev_i32_e32 v1, 31, v0
	v_mul_lo_u32 v2, s14, v1
	v_mul_lo_u32 v3, s15, v0
	v_mad_u64_u32 v[0:1], s[4:5], s14, v0, 0
	v_add3_u32 v1, v1, v2, v3
	v_lshl_add_u64 v[0:1], v[0:1], 1, v[10:11]
	s_waitcnt lgkmcnt(0)
	global_store_dwordx4 v[0:1], v[4:7], off sc1
	s_barrier
	s_cbranch_scc1 .LBB0_1159

.LBB0_1528:
	s_mul_hi_i32 s19, s14, s8
	s_mul_i32 s18, s14, s8
	s_ashr_i32 s9, s8, 31
	s_lshl_b64 s[18:19], s[18:19], 2
	v_ashrrev_i32_e32 v4, 5, v2
	s_add_u32 s16, s16, s18
	v_and_b32_e32 v5, -2, v4
	s_addc_u32 s17, s17, s19
	v_max_i32_e32 v152, 0, v22
	v_add_u32_e32 v6, 16, v5
	v_lshl_add_u64 v[0:1], v[152:153], 2, s[16:17]
	v_mad_i64_i32 v[6:7], s[16:17], s14, v6, 0
	v_lshl_add_u64 v[6:7], v[6:7], 2, v[0:1]
	global_load_dword v6, v[6:7], off
	v_add_u32_e32 v7, 17, v5
	v_mad_i64_i32 v[8:9], s[16:17], s14, v7, 0
	v_lshl_add_u64 v[8:9], v[8:9], 2, v[0:1]
	global_load_dword v7, v[8:9], off
	v_add_u32_e32 v8, 32, v5
	v_mad_i64_i32 v[8:9], s[16:17], s14, v8, 0
	v_lshl_add_u64 v[8:9], v[8:9], 2, v[0:1]
	global_load_dword v8, v[8:9], off
	v_add_u32_e32 v9, 33, v5
	v_mad_i64_i32 v[10:11], s[16:17], s14, v9, 0
	v_lshl_add_u64 v[10:11], v[10:11], 2, v[0:1]
	global_load_dword v9, v[10:11], off
	v_add_u32_e32 v10, 48, v5
	v_mad_i64_i32 v[10:11], s[16:17], s14, v10, 0
	v_lshl_add_u64 v[10:11], v[10:11], 2, v[0:1]
	global_load_dword v10, v[10:11], off
	v_add_u32_e32 v11, 49, v5
	v_mad_i64_i32 v[14:15], s[16:17], s14, v11, 0
	v_lshl_add_u64 v[14:15], v[14:15], 2, v[0:1]
	v_add_u32_e32 v12, 64, v5
	global_load_dword v11, v[14:15], off
	v_mad_i64_i32 v[14:15], s[16:17], s14, v12, 0
	v_lshl_add_u64 v[14:15], v[14:15], 2, v[0:1]
	global_load_dword v12, v[14:15], off
	v_add_u32_e32 v14, 0x41, v5
	v_mad_i64_i32 v[14:15], s[16:17], s14, v14, 0
	v_lshl_add_u64 v[14:15], v[14:15], 2, v[0:1]
	global_load_dword v14, v[14:15], off
	v_add_u32_e32 v15, 0x50, v5
	v_mad_i64_i32 v[16:17], s[16:17], s14, v15, 0
	v_lshl_add_u64 v[16:17], v[16:17], 2, v[0:1]
	global_load_dword v15, v[16:17], off
	v_add_u32_e32 v16, 0x51, v5
	v_mad_i64_i32 v[16:17], s[16:17], s14, v16, 0
	v_lshl_add_u64 v[16:17], v[16:17], 2, v[0:1]
	global_load_dword v16, v[16:17], off
	v_add_u32_e32 v17, 0x60, v5
	v_mad_i64_i32 v[18:19], s[16:17], s14, v17, 0
	v_lshl_add_u64 v[18:19], v[18:19], 2, v[0:1]
	global_load_dword v17, v[18:19], off
	v_add_u32_e32 v18, 0x61, v5
	v_mad_i64_i32 v[18:19], s[16:17], s14, v18, 0
	v_lshl_add_u64 v[18:19], v[18:19], 2, v[0:1]
	global_load_dword v18, v[18:19], off
	v_add_u32_e32 v19, 0x70, v5
	v_mad_i64_i32 v[20:21], s[16:17], s14, v19, 0
	v_lshl_add_u64 v[20:21], v[20:21], 2, v[0:1]
	global_load_dword v19, v[20:21], off
	v_add_u32_e32 v20, 0x71, v5
	v_mad_i64_i32 v[20:21], s[16:17], s14, v20, 0
	v_lshl_add_u64 v[20:21], v[20:21], 2, v[0:1]
	global_load_dword v20, v[20:21], off
	v_add_u32_e32 v21, 0x80, v5
	v_mad_i64_i32 v[24:25], s[16:17], s14, v21, 0
	v_lshl_add_u64 v[24:25], v[24:25], 2, v[0:1]
	v_add_u32_e32 v23, 0x81, v5
	global_load_dword v21, v[24:25], off
	v_mad_i64_i32 v[24:25], s[16:17], s14, v23, 0
	v_lshl_add_u64 v[24:25], v[24:25], 2, v[0:1]
	global_load_dword v23, v[24:25], off
	v_add_u32_e32 v24, 0x90, v5
	v_mad_i64_i32 v[24:25], s[16:17], s14, v24, 0
	v_lshl_add_u64 v[24:25], v[24:25], 2, v[0:1]
	global_load_dword v24, v[24:25], off
	v_add_u32_e32 v25, 0x91, v5
	v_mad_i64_i32 v[26:27], s[16:17], s14, v25, 0
	v_lshl_add_u64 v[26:27], v[26:27], 2, v[0:1]
	global_load_dword v25, v[26:27], off
	v_add_u32_e32 v26, 0xa0, v5
	v_mad_i64_i32 v[26:27], s[16:17], s14, v26, 0
	v_lshl_add_u64 v[26:27], v[26:27], 2, v[0:1]
	global_load_dword v28, v[26:27], off
	v_add_u32_e32 v26, 0xa1, v5
	v_mad_i64_i32 v[26:27], s[16:17], s14, v26, 0
	v_lshl_add_u64 v[26:27], v[26:27], 2, v[0:1]
	global_load_dword v29, v[26:27], off
	v_add_u32_e32 v26, 0xb0, v5
	v_mad_i64_i32 v[26:27], s[16:17], s14, v26, 0
	v_lshl_add_u64 v[26:27], v[26:27], 2, v[0:1]
	global_load_dword v30, v[26:27], off
	v_add_u32_e32 v26, 0xb1, v5
	v_mad_i64_i32 v[26:27], s[16:17], s14, v26, 0
	v_lshl_add_u64 v[26:27], v[26:27], 2, v[0:1]
	global_load_dword v31, v[26:27], off
	v_add_u32_e32 v26, 0xc0, v5
	v_mad_i64_i32 v[26:27], s[16:17], s14, v26, 0
	v_lshl_add_u64 v[26:27], v[26:27], 2, v[0:1]
	global_load_dword v32, v[26:27], off
	v_add_u32_e32 v26, 0xc1, v5
	v_mad_i64_i32 v[26:27], s[16:17], s14, v26, 0
	v_lshl_add_u64 v[26:27], v[26:27], 2, v[0:1]
	global_load_dword v33, v[26:27], off
	v_add_u32_e32 v26, 0xd0, v5
	v_mad_i64_i32 v[26:27], s[16:17], s14, v26, 0
	v_lshl_add_u64 v[26:27], v[26:27], 2, v[0:1]
	global_load_dword v34, v[26:27], off
	v_add_u32_e32 v26, 0xd1, v5
	v_mad_i64_i32 v[26:27], s[16:17], s14, v26, 0
	v_lshl_add_u64 v[26:27], v[26:27], 2, v[0:1]
	global_load_dword v35, v[26:27], off
	v_add_u32_e32 v26, 0xe0, v5
	v_mad_i64_i32 v[26:27], s[16:17], s14, v26, 0
	v_lshl_add_u64 v[26:27], v[26:27], 2, v[0:1]
	global_load_dword v36, v[26:27], off
	v_add_u32_e32 v26, 0xe1, v5
	v_mad_i64_i32 v[26:27], s[16:17], s14, v26, 0
	v_lshl_add_u64 v[26:27], v[26:27], 2, v[0:1]
	global_load_dword v37, v[26:27], off
	v_add_u32_e32 v26, 0xf0, v5
	v_mad_i64_i32 v[26:27], s[16:17], s14, v26, 0
	v_lshl_add_u64 v[26:27], v[26:27], 2, v[0:1]
	global_load_dword v38, v[26:27], off
	v_add_u32_e32 v26, 0xf1, v5
	v_mad_i64_i32 v[26:27], s[16:17], s14, v26, 0
	v_lshl_add_u64 v[26:27], v[26:27], 2, v[0:1]
	global_load_dword v39, v[26:27], off
	v_mad_i64_i32 v[26:27], s[16:17], s14, v5, 0
	v_lshl_add_u64 v[26:27], v[26:27], 2, v[0:1]
	v_cmp_gt_i32_e32 vcc, 0, v22
	global_load_dword v22, v[26:27], off
	v_or_b32_e32 v26, 1, v4
	v_mad_i64_i32 v[26:27], s[14:15], s14, v26, 0
	v_lshl_add_u64 v[0:1], v[26:27], 2, v[0:1]
	global_load_dword v0, v[0:1], off
	v_mul_u32_u24_e32 v13, 0x210, v13
	v_lshlrev_b32_e32 v1, 1, v5
	s_waitcnt vmcnt(0)
	v_cndmask_b32_e64 v5, v6, 0, vcc
	v_cndmask_b32_e64 v6, v7, 0, vcc
	v_add3_u32 v1, 0, v13, v1
	v_cvt_pk_bf16_f32 v5, v5, v6
	v_cndmask_b32_e64 v6, v11, 0, vcc
	s_lshl_b64 s[8:9], s[8:9], 1
	s_add_u32 s8, s12, s8
	s_addc_u32 s9, s13, s9
	v_cndmask_b32_e64 v22, v22, 0, vcc
	v_cndmask_b32_e64 v0, v0, 0, vcc
	v_cvt_pk_bf16_f32 v0, v22, v0
	ds_write2_b32 v1, v0, v5 offset1:8
	v_cndmask_b32_e64 v0, v8, 0, vcc
	v_cndmask_b32_e64 v5, v9, 0, vcc
	v_cvt_pk_bf16_f32 v0, v0, v5
	v_cndmask_b32_e64 v5, v10, 0, vcc
	v_cvt_pk_bf16_f32 v5, v5, v6
	ds_write2_b32 v1, v0, v5 offset0:16 offset1:24
	v_cndmask_b32_e64 v0, v12, 0, vcc
	v_cndmask_b32_e64 v5, v14, 0, vcc
	v_cvt_pk_bf16_f32 v0, v0, v5
	v_cndmask_b32_e64 v5, v15, 0, vcc
	v_cndmask_b32_e64 v6, v16, 0, vcc
	v_cvt_pk_bf16_f32 v5, v5, v6
	ds_write2_b32 v1, v0, v5 offset0:32 offset1:40
	v_cndmask_b32_e64 v0, v17, 0, vcc
	v_cndmask_b32_e64 v5, v18, 0, vcc
	v_cvt_pk_bf16_f32 v0, v0, v5
	v_cndmask_b32_e64 v5, v19, 0, vcc
	v_cndmask_b32_e64 v6, v20, 0, vcc
	v_cvt_pk_bf16_f32 v5, v5, v6
	ds_write2_b32 v1, v0, v5 offset0:48 offset1:56
	v_cndmask_b32_e64 v0, v21, 0, vcc
	v_cndmask_b32_e64 v5, v23, 0, vcc
	v_cvt_pk_bf16_f32 v0, v0, v5
	v_cndmask_b32_e64 v5, v24, 0, vcc
	v_cndmask_b32_e64 v6, v25, 0, vcc
	v_cvt_pk_bf16_f32 v5, v5, v6
	ds_write2_b32 v1, v0, v5 offset0:64 offset1:72
	v_cndmask_b32_e64 v0, v28, 0, vcc
	v_cndmask_b32_e64 v5, v29, 0, vcc
	v_cvt_pk_bf16_f32 v0, v0, v5
	v_cndmask_b32_e64 v5, v30, 0, vcc
	v_cndmask_b32_e64 v6, v31, 0, vcc
	v_cvt_pk_bf16_f32 v5, v5, v6
	ds_write2_b32 v1, v0, v5 offset0:80 offset1:88
	v_cndmask_b32_e64 v0, v32, 0, vcc
	v_cndmask_b32_e64 v5, v33, 0, vcc
	v_cvt_pk_bf16_f32 v0, v0, v5
	v_cndmask_b32_e64 v5, v34, 0, vcc
	v_cndmask_b32_e64 v6, v35, 0, vcc
	v_cvt_pk_bf16_f32 v5, v5, v6
	ds_write2_b32 v1, v0, v5 offset0:96 offset1:104
	v_cndmask_b32_e64 v0, v36, 0, vcc
	v_cndmask_b32_e64 v5, v37, 0, vcc
	v_cvt_pk_bf16_f32 v0, v0, v5
	v_cndmask_b32_e64 v5, v38, 0, vcc
	v_cndmask_b32_e64 v6, v39, 0, vcc
	v_cvt_pk_bf16_f32 v5, v5, v6
	ds_write2_b32 v1, v0, v5 offset0:112 offset1:120
	v_lshlrev_b32_e32 v0, 4, v2
	v_and_b32_e32 v152, 0x1f0, v0
	v_add_u32_e32 v0, 0, v152
	v_lshl_add_u64 v[10:11], s[8:9], 0, v[152:153]
	v_mad_u64_u32 v[6:7], s[8:9], v4, s69, v[0:1]
	s_waitcnt lgkmcnt(0)
	s_barrier
	ds_read_b128 v[6:9], v6
	v_add_u32_e32 v1, v3, v4
	v_mad_i64_i32 v[4:5], s[8:9], s10, v1, 0
	v_add_u32_e32 v1, 0x200, v2
	v_lshl_add_u64 v[4:5], v[4:5], 1, v[10:11]
	v_ashrrev_i32_e32 v1, 5, v1
	s_waitcnt lgkmcnt(0)
	global_store_dwordx4 v[4:5], v[6:9], off sc1
	v_mad_u64_u32 v[4:5], s[8:9], v1, s69, v[0:1]
	ds_read_b128 v[4:7], v4
	v_add_u32_e32 v1, v3, v1
	v_mad_i64_i32 v[8:9], s[8:9], s10, v1, 0
	v_add_u32_e32 v1, 0x400, v2
	v_lshl_add_u64 v[8:9], v[8:9], 1, v[10:11]
	v_ashrrev_i32_e32 v1, 5, v1
	s_waitcnt lgkmcnt(0)
	global_store_dwordx4 v[8:9], v[4:7], off sc1
	s_nop 1
	v_mad_u64_u32 v[4:5], s[8:9], v1, s69, v[0:1]
	ds_read_b128 v[4:7], v4
	v_add_u32_e32 v1, v3, v1
	v_mad_i64_i32 v[8:9], s[8:9], s10, v1, 0
	v_add_u32_e32 v1, 0x600, v2
	v_ashrrev_i32_e32 v2, 5, v1
	v_lshl_add_u64 v[8:9], v[8:9], 1, v[10:11]
	v_mad_u64_u32 v[0:1], s[8:9], v2, s69, v[0:1]
	s_waitcnt lgkmcnt(0)
	global_store_dwordx4 v[8:9], v[4:7], off sc1
	ds_read_b128 v[4:7], v0
	v_add_u32_e32 v0, v3, v2
	v_mad_i64_i32 v[0:1], s[8:9], s10, v0, 0
	s_add_i32 s8, s2, 0x80
	v_readlane_b32 s98, v254, 22
	v_lshl_add_u64 v[0:1], v[0:1], 1, v[10:11]
	s_cmp_eq_u32 s98, 0
	s_movk_i32 s99, 0x190
	s_cselect_b32 s98, 0x280, s99
	s_cmp_lt_i32 s2, s98
	s_mov_b32 s2, s8
	s_waitcnt lgkmcnt(0)
	global_store_dwordx4 v[0:1], v[4:7], off sc1
	s_barrier
	s_cbranch_scc0 .LBB0_1498

.LBB0_1561:
	v_cndmask_b32_e64 v0, v0, 0, s[8:9]
	v_cndmask_b32_e64 v1, v1, 0, s[8:9]
	v_cvt_pk_bf16_f32 v2, v4, v5
	v_cvt_pk_bf16_f32 v0, v0, v1
	s_ashr_i32 s5, s4, 31
	ds_write2_b32 v20, v2, v0 offset0:112 offset1:120
	v_lshlrev_b32_e32 v0, 4, v22
	s_lshl_b64 s[4:5], s[4:5], 1
	v_and_b32_e32 v152, 0x1f0, v0
	s_add_u32 s4, s14, s4
	v_add_u32_e32 v4, 0, v152
	s_addc_u32 s5, s15, s5
	v_lshl_add_u64 v[6:7], s[4:5], 0, v[152:153]
	v_mad_u64_u32 v[0:1], s[4:5], v25, s69, v[4:5]
	s_waitcnt lgkmcnt(0)
	s_barrier
	ds_read_b128 v[0:3], v0
	v_add_u32_e32 v5, v24, v25
	v_ashrrev_i32_e32 v8, 31, v5
	v_mul_lo_u32 v10, s12, v8
	v_mul_lo_u32 v11, s13, v5
	v_mad_u64_u32 v[8:9], s[4:5], s12, v5, 0
	v_add3_u32 v9, v9, v10, v11
	v_lshl_add_u64 v[8:9], v[8:9], 1, v[6:7]
	s_waitcnt lgkmcnt(0)
	global_store_dwordx4 v[8:9], v[0:3], off sc1
	s_add_i32 s26, s26, 64
	s_add_i32 s2, s2, 64
	v_add_u32_e32 v0, 0x200, v22
	v_ashrrev_i32_e32 v5, 5, v0
	v_mad_u64_u32 v[0:1], s[4:5], v5, s69, v[4:5]
	ds_read_b128 v[0:3], v0
	v_add_u32_e32 v5, v24, v5
	v_ashrrev_i32_e32 v8, 31, v5
	v_mul_lo_u32 v10, s12, v8
	v_mul_lo_u32 v11, s13, v5
	v_mad_u64_u32 v[8:9], s[4:5], s12, v5, 0
	v_add3_u32 v9, v9, v10, v11
	v_lshl_add_u64 v[8:9], v[8:9], 1, v[6:7]
	s_waitcnt lgkmcnt(0)
	global_store_dwordx4 v[8:9], v[0:3], off sc1
	s_cmpk_lt_i32 s27, 0x180
	s_nop 0
	v_add_u32_e32 v0, 0x400, v22
	v_ashrrev_i32_e32 v5, 5, v0
	v_mad_u64_u32 v[0:1], s[4:5], v5, s69, v[4:5]
	ds_read_b128 v[0:3], v0
	v_add_u32_e32 v5, v24, v5
	v_ashrrev_i32_e32 v8, 31, v5
	v_mul_lo_u32 v10, s12, v8
	v_mul_lo_u32 v11, s13, v5
	v_mad_u64_u32 v[8:9], s[4:5], s12, v5, 0
	v_add3_u32 v9, v9, v10, v11
	v_lshl_add_u64 v[8:9], v[8:9], 1, v[6:7]
	s_waitcnt lgkmcnt(0)
	global_store_dwordx4 v[8:9], v[0:3], off sc1
	s_nop 1
	v_add_u32_e32 v0, 0x600, v22
	v_ashrrev_i32_e32 v5, 5, v0
	v_mad_u64_u32 v[0:1], s[4:5], v5, s69, v[4:5]
	ds_read_b128 v[0:3], v0
	v_add_u32_e32 v4, v24, v5
	v_ashrrev_i32_e32 v5, 31, v4
	v_mul_lo_u32 v8, s12, v5
	v_mul_lo_u32 v9, s13, v4
	v_mad_u64_u32 v[4:5], s[4:5], s12, v4, 0
	v_add3_u32 v5, v5, v8, v9
	v_lshl_add_u64 v[4:5], v[4:5], 1, v[6:7]
	s_waitcnt lgkmcnt(0)
	global_store_dwordx4 v[4:5], v[0:3], off sc1
	s_barrier
	s_cbranch_scc0 .LBB0_1499
